# in-proj quad start: first K-tile LDS-DMA loads issued before the row-scale pass (row scales are only read by the epilogue), row-scale block on renamed registers
# baseline (speedup 1.0000x reference)
.LBB0_113:
	v_mov_b32_e32 v14, v243
	s_and_b32 s3, s12, 1
	v_ashrrev_i32_e32 v0, 31, v14
	v_lshrrev_b32_e32 v0, 26, v0
	v_add_u32_e32 v0, v14, v0
	v_ashrrev_i32_e32 v10, 6, v0
	v_bfe_i32 v0, v14, 27, 1
	v_lshlrev_b32_e32 v2, 4, v14
	v_lshrrev_b32_e32 v0, 22, v0
	v_add_u32_e32 v0, v2, v0
	v_and_b32_e32 v0, 0xfffffc00, v0
	v_sub_u32_e32 v0, v2, v0
	v_lshrrev_b32_e32 v3, 4, v0
	v_bitop3_b32 v0, v3, v0, 32 bitop3:0x6c
	v_ashrrev_i32_e32 v4, 31, v0
	v_lshrrev_b32_e32 v4, 26, v4
	v_add_u32_e32 v4, v0, v4
	v_lshlrev_b32_e32 v3, 3, v10
	v_ashrrev_i32_e32 v11, 6, v4
	v_and_b32_e32 v4, 0xc0, v4
	v_and_b32_e32 v3, -16, v3
	v_sub_u32_e32 v0, v0, v4
	s_and_b32 s4, s11, 2
	s_lshl_b64 s[0:1], s[78:79], 25
	v_readlane_b32 s2, v255, 6
	v_add_u32_e32 v3, v11, v3
	v_ashrrev_i16_sdwa v0, v254, sext(v0) dst_sel:DWORD dst_unused:UNUSED_PAD src0_sel:DWORD src1_sel:BYTE_0
	s_add_u32 s28, s2, s0
	v_lshlrev_b32_e32 v5, 5, v10
	v_bfe_i32 v12, v0, 0, 16
	v_lshlrev_b32_e32 v0, 1, v3
	v_lshrrev_b32_e32 v4, 2, v3
	v_and_b32_e32 v6, 3, v11
	s_mov_b32 s2, 0xfffe0
	v_and_b32_e32 v5, 32, v5
	v_and_b32_e32 v0, 24, v0
	v_and_b32_e32 v4, 4, v4
	v_and_or_b32 v6, v3, s2, v6
	v_or3_b32 v0, v6, v4, v0
	v_add_lshl_u32 v4, v5, v12, 1
	v_add_u32_e32 v2, 0x2000, v2
	v_lshl_add_u32 v130, v3, 12, v4
	v_ashrrev_i32_e32 v3, 31, v2
	v_lshrrev_b32_e32 v3, 22, v3
	v_add_u32_e32 v3, v2, v3
	v_ashrrev_i32_e32 v13, 10, v3
	v_mul_i32_i24_e32 v3, 0x400, v13
	v_sub_u32_e32 v2, v2, v3
	v_lshrrev_b32_e32 v3, 4, v2
	v_bitop3_b32 v2, v3, v2, 32 bitop3:0x6c
	v_lshl_add_u32 v0, v0, 12, v4
	v_ashrrev_i32_e32 v4, 31, v2
	v_readlane_b32 s0, v255, 7
	v_lshrrev_b32_e32 v4, 26, v4
	s_addc_u32 s29, s0, s1
	v_lshlrev_b32_e32 v3, 3, v13
	v_add_u32_e32 v4, v2, v4
	s_or_b32 s3, s3, s4
	v_readfirstlane_b32 s0, v14
	v_and_b32_e32 v3, -16, v3
	v_ashrrev_i32_e32 v15, 6, v4
	s_and_b32 s30, s11, 1
	s_lshl_b32 s34, s3, 1
	s_ashr_i32 s1, s0, 6
	v_add_u32_e32 v3, v15, v3
	v_and_b32_e32 v4, 0xc0, v4
	v_and_b32_e32 v6, 3, v15
	s_or_b32 s8, s34, s30
	s_ashr_i32 s11, s10, 31
	v_sub_u32_e32 v2, v2, v4
	v_and_or_b32 v6, v3, s2, v6
	s_ashr_i32 s2, s0, 8
	s_lshl_b32 s31, s1, 10
	s_lshl_b64 s[4:5], s[10:11], 20
	s_lshl_b32 s3, s8, 20
	v_ashrrev_i16_sdwa v2, v254, sext(v2) dst_sel:DWORD dst_unused:UNUSED_PAD src0_sel:DWORD src1_sel:BYTE_0
	s_add_u32 s12, s28, s3
	v_lshlrev_b32_e32 v5, 5, v13
	v_bfe_i32 v16, v2, 0, 16
	v_lshlrev_b32_e32 v2, 1, v3
	v_lshrrev_b32_e32 v4, 2, v3
	s_addc_u32 s13, s29, 0
	s_add_i32 s11, s31, 0
	v_and_b32_e32 v5, 32, v5
	v_and_b32_e32 v2, 24, v2
	v_and_b32_e32 v4, 4, v4
	s_add_i32 m0, s11, 0x10000
	v_or3_b32 v2, v6, v4, v2
	v_add_lshl_u32 v4, v5, v16, 1
	global_load_lds_dwordx4 v0, s[12:13]
	s_add_i32 m0, s11, 0x12000
	v_lshl_add_u32 v134, v2, 12, v4
	s_add_u32 s6, s12, 0x80000
	global_load_lds_dwordx4 v134, s[12:13]
	s_addc_u32 s7, s13, 0
	s_add_i32 m0, s11, 0x14000
	v_lshl_add_u32 v132, v3, 12, v4
	global_load_lds_dwordx4 v0, s[6:7]
	s_add_i32 m0, s11, 0x16000
	s_add_u32 s14, s44, s4
	s_addc_u32 s15, s45, s5
	s_add_i32 s35, s11, 0x2000
	global_load_lds_dwordx4 v134, s[6:7]
	s_mov_b32 m0, s11
	s_add_u32 s4, s14, 0x80000
	global_load_lds_dwordx4 v130, s[14:15]
	s_mov_b32 m0, s35
	s_addc_u32 s5, s15, 0
	s_add_i32 s36, s11, 0x4000
	global_load_lds_dwordx4 v132, s[14:15]
	s_mov_b32 m0, s36
	s_add_i32 s37, s11, 0x6000
	global_load_lds_dwordx4 v130, s[4:5]
	s_mov_b32 m0, s37
	s_cmp_eq_u32 s2, 1
	global_load_lds_dwordx4 v132, s[4:5]
	v_mov_b32_e32 v135, v1
	v_mov_b32_e32 v131, v1
	v_mov_b32_e32 v133, v1
	s_cselect_b64 s[16:17], -1, 0
	v_lshl_add_u64 v[8:9], s[12:13], 0, v[0:1]
	v_lshl_add_u64 v[6:7], s[12:13], 0, v[134:135]
	v_lshl_add_u64 v[4:5], s[14:15], 0, v[130:131]
	v_lshl_add_u64 v[2:3], s[14:15], 0, v[132:133]
	v_mov_b32_e32 v177, 0
	v_mov_b32_e32 v196, v243
	v_readlane_b32 s82, v255, 10
	v_ashrrev_i32_e32 v197, 1, v196
	v_lshl_add_u32 v178, s10, 8, v197
	v_ashrrev_i32_e32 v179, 31, v178
	v_and_b32_e32 v198, 1, v196
	v_lshlrev_b64 v[178:179], 7, v[178:179]
	v_readlane_b32 s83, v255, 11
	v_lshlrev_b32_e32 v176, 6, v198
	v_cmp_eq_u32_e64 s[86:87], 0, v198
	v_lshl_add_u64 v[178:179], s[82:83], 0, v[178:179]
	v_lshl_add_u64 v[178:179], v[178:179], 0, v[176:177]
	global_load_dwordx4 v[180:183], v[178:179], off
	global_load_dwordx4 v[184:187], v[178:179], off offset:16
	global_load_dwordx4 v[188:191], v[178:179], off offset:32
	global_load_dwordx4 v[192:195], v[178:179], off offset:48
	v_lshlrev_b32_e32 v176, 2, v196
	v_bfrev_b32_e32 v178, 0.5
	v_bitop3_b32 v178, v176, 4, v178 bitop3:0x6c
	s_add_i32 s82, 0, 0x20000
	s_waitcnt vmcnt(0)
	v_pk_add_f32 v[182:183], v[182:183], v[186:187]
	v_pk_add_f32 v[180:181], v[180:181], v[184:185]
	v_pk_add_f32 v[184:185], v[190:191], v[194:195]
	v_pk_add_f32 v[186:187], v[188:189], v[192:193]
	v_pk_add_f32 v[182:183], v[182:183], v[184:185]
	v_pk_add_f32 v[180:181], v[180:181], v[186:187]
	v_add_f32_e32 v179, v182, v183
	v_add_f32_e32 v176, v180, v181
	v_add_f32_e32 v179, v176, v179
	ds_bpermute_b32 v180, v178, v179
	v_lshl_add_u32 v176, v197, 2, s82
	s_and_saveexec_b64 s[82:83], s[86:87]
	s_cbranch_execz .LBB0_115
	s_waitcnt lgkmcnt(0)
	v_add_f32_e32 v180, v179, v180
	v_fmamk_f32 v180, v180, 0x3a000000, v252
	s_mov_b32 s84, 0xf800000
	v_mul_f32_e32 v181, 0x4f800000, v180
	v_cmp_gt_f32_e32 vcc, s84, v180
	s_nop 1
	v_cndmask_b32_e32 v180, v180, v181, vcc
	v_sqrt_f32_e32 v181, v180
	s_nop 0
	v_add_u32_e32 v182, -1, v181
	v_fma_f32 v184, -v182, v181, v180
	v_add_u32_e32 v183, 1, v181
	v_cmp_ge_f32_e64 s[88:89], 0, v184
	s_nop 1
	v_cndmask_b32_e64 v182, v181, v182, s[88:89]
	v_fma_f32 v181, -v183, v181, v180
	v_cmp_lt_f32_e64 s[88:89], 0, v181
	s_nop 1
	v_cndmask_b32_e64 v181, v182, v183, s[88:89]
	v_mul_f32_e32 v182, 0x37800000, v181
	v_cndmask_b32_e32 v181, v181, v182, vcc
	v_cmp_class_f32_e32 vcc, v180, v253
	s_nop 1
	v_cndmask_b32_e32 v180, v181, v180, vcc
	v_div_scale_f32 v181, s[84:85], v180, v180, 1.0
	v_rcp_f32_e32 v182, v181
	s_nop 0
	v_fma_f32 v183, -v181, v182, 1.0
	v_fmac_f32_e32 v182, v183, v182
	v_div_scale_f32 v183, vcc, 1.0, v180, 1.0
	v_mul_f32_e32 v184, v183, v182
	v_fma_f32 v185, -v181, v184, v183
	v_fmac_f32_e32 v184, v185, v182
	v_fma_f32 v181, -v181, v184, v183
	v_div_fmas_f32 v181, v181, v182, v184
	v_div_fixup_f32 v180, v181, v180, 1.0
	ds_write_b32 v176, v180
.LBB0_115:
	s_or_b64 exec, exec, s[82:83]
	s_waitcnt lgkmcnt(0)
	ds_bpermute_b32 v180, v178, v179
	s_and_saveexec_b64 s[82:83], s[86:87]
	s_cbranch_execz .LBB0_117
	s_waitcnt lgkmcnt(0)
	v_add_f32_e32 v180, v179, v180
	v_fmamk_f32 v180, v180, 0x3a000000, v252
	s_mov_b32 s84, 0xf800000
	v_mul_f32_e32 v181, 0x4f800000, v180
	v_cmp_gt_f32_e32 vcc, s84, v180
	s_nop 1
	v_cndmask_b32_e32 v180, v180, v181, vcc
	v_sqrt_f32_e32 v181, v180
	s_nop 0
	v_add_u32_e32 v182, -1, v181
	v_fma_f32 v184, -v182, v181, v180
	v_add_u32_e32 v183, 1, v181
	v_cmp_ge_f32_e64 s[88:89], 0, v184
	s_nop 1
	v_cndmask_b32_e64 v182, v181, v182, s[88:89]
	v_fma_f32 v181, -v183, v181, v180
	v_cmp_lt_f32_e64 s[88:89], 0, v181
	s_nop 1
	v_cndmask_b32_e64 v181, v182, v183, s[88:89]
	v_mul_f32_e32 v182, 0x37800000, v181
	v_cndmask_b32_e32 v181, v181, v182, vcc
	v_cmp_class_f32_e32 vcc, v180, v253
	s_nop 1
	v_cndmask_b32_e32 v180, v181, v180, vcc
	v_div_scale_f32 v181, s[84:85], v180, v180, 1.0
	v_rcp_f32_e32 v182, v181
	s_nop 0
	v_fma_f32 v183, -v181, v182, 1.0
	v_fmac_f32_e32 v182, v183, v182
	v_div_scale_f32 v183, vcc, 1.0, v180, 1.0
	v_mul_f32_e32 v184, v183, v182
	v_fma_f32 v185, -v181, v184, v183
	v_fmac_f32_e32 v184, v185, v182
	v_fma_f32 v181, -v181, v184, v183
	v_div_fmas_f32 v181, v181, v182, v184
	v_div_fixup_f32 v180, v181, v180, 1.0
	ds_write_b32 v176, v180 offset:1024
.LBB0_117:
	s_or_b64 exec, exec, s[82:83]
	s_waitcnt lgkmcnt(0)
	ds_bpermute_b32 v180, v178, v179
	s_and_saveexec_b64 s[82:83], s[86:87]
	s_cbranch_execz .LBB0_119
	s_waitcnt lgkmcnt(0)
	v_add_f32_e32 v180, v179, v180
	v_fmamk_f32 v180, v180, 0x3a000000, v252
	s_mov_b32 s84, 0xf800000
	v_mul_f32_e32 v181, 0x4f800000, v180
	v_cmp_gt_f32_e32 vcc, s84, v180
	s_nop 1
	v_cndmask_b32_e32 v180, v180, v181, vcc
	v_sqrt_f32_e32 v181, v180
	s_nop 0
	v_add_u32_e32 v182, -1, v181
	v_fma_f32 v184, -v182, v181, v180
	v_add_u32_e32 v183, 1, v181
	v_cmp_ge_f32_e64 s[88:89], 0, v184
	s_nop 1
	v_cndmask_b32_e64 v182, v181, v182, s[88:89]
	v_fma_f32 v181, -v183, v181, v180
	v_cmp_lt_f32_e64 s[88:89], 0, v181
	s_nop 1
	v_cndmask_b32_e64 v181, v182, v183, s[88:89]
	v_mul_f32_e32 v182, 0x37800000, v181
	v_cndmask_b32_e32 v181, v181, v182, vcc
	v_cmp_class_f32_e32 vcc, v180, v253
	s_nop 1
	v_cndmask_b32_e32 v180, v181, v180, vcc
	v_div_scale_f32 v181, s[84:85], v180, v180, 1.0
	v_rcp_f32_e32 v182, v181
	s_nop 0
	v_fma_f32 v183, -v181, v182, 1.0
	v_fmac_f32_e32 v182, v183, v182
	v_div_scale_f32 v183, vcc, 1.0, v180, 1.0
	v_mul_f32_e32 v184, v183, v182
	v_fma_f32 v185, -v181, v184, v183
	v_fmac_f32_e32 v184, v185, v182
	v_fma_f32 v181, -v181, v184, v183
	v_div_fmas_f32 v181, v181, v182, v184
	v_div_fixup_f32 v180, v181, v180, 1.0
	ds_write_b32 v176, v180 offset:2048
.LBB0_119:
	s_or_b64 exec, exec, s[82:83]
	ds_bpermute_b32 v178, v178, v179
	s_and_saveexec_b64 s[82:83], s[86:87]
	s_cbranch_execz .LBB0_121
	s_waitcnt lgkmcnt(0)
	v_add_f32_e32 v178, v179, v178
	v_fmamk_f32 v178, v178, 0x3a000000, v252
	s_mov_b32 s84, 0xf800000
	v_mul_f32_e32 v179, 0x4f800000, v178
	v_cmp_gt_f32_e32 vcc, s84, v178
	s_nop 1
	v_cndmask_b32_e32 v178, v178, v179, vcc
	v_sqrt_f32_e32 v179, v178
	s_nop 0
	v_add_u32_e32 v180, -1, v179
	v_fma_f32 v182, -v180, v179, v178
	v_add_u32_e32 v181, 1, v179
	v_cmp_ge_f32_e64 s[86:87], 0, v182
	s_nop 1
	v_cndmask_b32_e64 v180, v179, v180, s[86:87]
	v_fma_f32 v179, -v181, v179, v178
	v_cmp_lt_f32_e64 s[86:87], 0, v179
	s_nop 1
	v_cndmask_b32_e64 v179, v180, v181, s[86:87]
	v_mul_f32_e32 v180, 0x37800000, v179
	v_cndmask_b32_e32 v179, v179, v180, vcc
	v_cmp_class_f32_e32 vcc, v178, v253
	s_nop 1
	v_cndmask_b32_e32 v178, v179, v178, vcc
	v_div_scale_f32 v179, s[84:85], v178, v178, 1.0
	v_rcp_f32_e32 v180, v179
	s_nop 0
	v_fma_f32 v181, -v179, v180, 1.0
	v_fmac_f32_e32 v180, v181, v180
	v_div_scale_f32 v181, vcc, 1.0, v178, 1.0
	v_mul_f32_e32 v182, v181, v180
	v_fma_f32 v183, -v179, v182, v181
	v_fmac_f32_e32 v182, v183, v180
	v_fma_f32 v179, -v179, v182, v181
	v_div_fmas_f32 v179, v179, v180, v182
	v_div_fixup_f32 v178, v179, v178, 1.0
	ds_write_b32 v176, v178 offset:3072
.LBB0_121:
	s_or_b64 exec, exec, s[82:83]
	s_waitcnt lgkmcnt(0)
	s_barrier
	s_and_b64 vcc, exec, s[16:17]
	s_cbranch_vccz .LBB0_123
	s_barrier
